# v3 plus softmax exp/sum block rewritten with packed f32 adds (in-place exps, P fragments packed in place)
# speedup vs baseline: 1.0022x; 1.0022x over previous
; DI f32x16 mfma32(bf16x8 a, bf16x8 b, f32x16 c) { return __builtin_amdgcn_mfma_f32_32x32x16_bf16(a, b, c, 0, 0, 0); }
; DI s16x4 vtr(lptr p) { return __builtin_bit_cast(s16x4, __builtin_amdgcn_ds_read_tr16_b64_v4i16((LAS s16x4*)p)); }
; template <int DQK, bool FOX>
; DI void attn_unit(const bf16_t* P, int pitch, int b, int qb, int qcol, int kcol, int vcol, bf16_t* Out, int opitch, int ocol, int gcol, const float* cum, lptr lds) {
;     ...
;             const float m_new = fmaxf(m_run, mx);
;             const float alpha = __builtin_amdgcn_exp2f(m_run - m_new);
;             const bool changed = __builtin_amdgcn_ballot_w64(m_new > m_run) != 0ull;
;             m_run = m_new;
;             float ls = 0.f;
; #pragma unroll
;             for (int t2 = 0; t2 < 2; ++t2)
; #pragma unroll
;                 for (int i = 0; i < 16; ++i) { const float e = __builtin_amdgcn_exp2f(pp[t2][i] - m_new); pp[t2][i] = e; ls += e; }
;             l_run = l_run * alpha + ls;
;             if (changed) {
; #pragma unroll
;                 for (int d = 0; d < 4; ++d) O[d] *= alpha;
;             }
;             bf16x8 pf[4];
; #pragma unroll
;             for (int s = 0; s < 4; ++s) pf[s] = pack8(pp[s >> 1], s & 1);
; #pragma unroll
;             for (int d = 0; d < 4; ++d)
; #pragma unroll
;                 for (int s = 0; s < 4; ++s) {
;                     const s16x4 lo = vtr(lds + (OFF_V + buf * REG + (16 * s) * 256) + vx[d]), hi = vtr(lds + (OFF_V + buf * REG + (16 * s + 8) * 256) + vx[d]);
;                     const bf16x8 vf = __builtin_shufflevector(lo, hi, 0, 1, 2, 3, 4, 5, 6, 7);
;                     O[d] = mfma32(vf, pf[s], O[d]);
.LBB0_344:
	v_pk_add_f32 v[82:83], v[82:83], v[182:183] op_sel:[0,1] op_sel_hi:[1,1] neg_lo:[0,1] neg_hi:[0,1]
	v_pk_add_f32 v[84:85], v[84:85], v[182:183] op_sel:[0,1] op_sel_hi:[1,1] neg_lo:[0,1] neg_hi:[0,1]
	v_pk_add_f32 v[86:87], v[86:87], v[182:183] op_sel:[0,1] op_sel_hi:[1,1] neg_lo:[0,1] neg_hi:[0,1]
	v_pk_add_f32 v[88:89], v[88:89], v[182:183] op_sel:[0,1] op_sel_hi:[1,1] neg_lo:[0,1] neg_hi:[0,1]
	v_pk_add_f32 v[90:91], v[90:91], v[182:183] op_sel:[0,1] op_sel_hi:[1,1] neg_lo:[0,1] neg_hi:[0,1]
	v_pk_add_f32 v[92:93], v[92:93], v[182:183] op_sel:[0,1] op_sel_hi:[1,1] neg_lo:[0,1] neg_hi:[0,1]
	v_pk_add_f32 v[94:95], v[94:95], v[182:183] op_sel:[0,1] op_sel_hi:[1,1] neg_lo:[0,1] neg_hi:[0,1]
	v_pk_add_f32 v[96:97], v[96:97], v[182:183] op_sel:[0,1] op_sel_hi:[1,1] neg_lo:[0,1] neg_hi:[0,1]
	v_pk_add_f32 v[66:67], v[66:67], v[182:183] op_sel:[0,1] op_sel_hi:[1,1] neg_lo:[0,1] neg_hi:[0,1]
	v_pk_add_f32 v[68:69], v[68:69], v[182:183] op_sel:[0,1] op_sel_hi:[1,1] neg_lo:[0,1] neg_hi:[0,1]
	v_pk_add_f32 v[70:71], v[70:71], v[182:183] op_sel:[0,1] op_sel_hi:[1,1] neg_lo:[0,1] neg_hi:[0,1]
	v_pk_add_f32 v[72:73], v[72:73], v[182:183] op_sel:[0,1] op_sel_hi:[1,1] neg_lo:[0,1] neg_hi:[0,1]
	v_pk_add_f32 v[74:75], v[74:75], v[182:183] op_sel:[0,1] op_sel_hi:[1,1] neg_lo:[0,1] neg_hi:[0,1]
	v_pk_add_f32 v[76:77], v[76:77], v[182:183] op_sel:[0,1] op_sel_hi:[1,1] neg_lo:[0,1] neg_hi:[0,1]
	v_pk_add_f32 v[78:79], v[78:79], v[182:183] op_sel:[0,1] op_sel_hi:[1,1] neg_lo:[0,1] neg_hi:[0,1]
	v_pk_add_f32 v[80:81], v[80:81], v[182:183] op_sel:[0,1] op_sel_hi:[1,1] neg_lo:[0,1] neg_hi:[0,1]
	v_exp_f32_e32 v82, v82
	v_exp_f32_e32 v83, v83
	v_exp_f32_e32 v84, v84
	v_exp_f32_e32 v85, v85
	v_exp_f32_e32 v86, v86
	v_exp_f32_e32 v87, v87
	v_exp_f32_e32 v88, v88
	v_exp_f32_e32 v89, v89
	v_exp_f32_e32 v90, v90
	v_exp_f32_e32 v91, v91
	v_exp_f32_e32 v92, v92
	v_exp_f32_e32 v93, v93
	v_exp_f32_e32 v94, v94
	v_exp_f32_e32 v95, v95
	v_exp_f32_e32 v96, v96
	v_exp_f32_e32 v97, v97
	v_exp_f32_e32 v66, v66
	v_exp_f32_e32 v67, v67
	v_exp_f32_e32 v68, v68
	v_exp_f32_e32 v69, v69
	v_exp_f32_e32 v70, v70
	v_exp_f32_e32 v71, v71
	v_exp_f32_e32 v72, v72
	v_exp_f32_e32 v73, v73
	v_exp_f32_e32 v74, v74
	v_exp_f32_e32 v75, v75
	v_exp_f32_e32 v76, v76
	v_exp_f32_e32 v77, v77
	v_exp_f32_e32 v78, v78
	v_exp_f32_e32 v79, v79
	v_exp_f32_e32 v80, v80
	v_exp_f32_e32 v81, v81
	v_pk_add_f32 v[184:185], v[82:83], v[84:85]
	v_pk_add_f32 v[184:185], v[184:185], v[86:87]
	v_pk_add_f32 v[184:185], v[184:185], v[88:89]
	v_pk_add_f32 v[184:185], v[184:185], v[90:91]
	v_pk_add_f32 v[184:185], v[184:185], v[92:93]
	v_pk_add_f32 v[184:185], v[184:185], v[94:95]
	v_pk_add_f32 v[184:185], v[184:185], v[96:97]
	v_pk_add_f32 v[184:185], v[184:185], v[66:67]
	v_pk_add_f32 v[184:185], v[184:185], v[68:69]
	v_pk_add_f32 v[184:185], v[184:185], v[70:71]
	v_pk_add_f32 v[184:185], v[184:185], v[72:73]
	v_pk_add_f32 v[184:185], v[184:185], v[74:75]
	v_pk_add_f32 v[184:185], v[184:185], v[76:77]
	v_pk_add_f32 v[184:185], v[184:185], v[78:79]
	v_pk_add_f32 v[184:185], v[184:185], v[80:81]
	v_add_f32_e32 v184, v184, v185
	v_fmac_f32_e32 v184, v181, v0
	v_mov_b32_e32 v181, v184
	v_cvt_pk_bf16_f32 v82, v82, v83
	v_cvt_pk_bf16_f32 v83, v84, v85
	v_cvt_pk_bf16_f32 v84, v86, v87
	v_cvt_pk_bf16_f32 v85, v88, v89
	v_cvt_pk_bf16_f32 v86, v90, v91
	v_cvt_pk_bf16_f32 v87, v92, v93
	v_cvt_pk_bf16_f32 v88, v94, v95
	v_cvt_pk_bf16_f32 v89, v96, v97
	v_cvt_pk_bf16_f32 v66, v66, v67
	v_cvt_pk_bf16_f32 v67, v68, v69
	v_cvt_pk_bf16_f32 v68, v70, v71
	v_cvt_pk_bf16_f32 v69, v72, v73
	v_cvt_pk_bf16_f32 v70, v74, v75
	v_cvt_pk_bf16_f32 v71, v76, v77
	v_cvt_pk_bf16_f32 v72, v78, v79
	v_cvt_pk_bf16_f32 v73, v80, v81
	s_waitcnt lgkmcnt(15)
	v_mfma_f32_32x32x16_bf16 v[50:65], v[212:215], v[82:85], v[50:65]
	ds_read_b64_tr_b16 v[212:213], v160 offset:20480
	ds_read_b64_tr_b16 v[214:215], v160 offset:22528
	s_waitcnt lgkmcnt(15)
	v_mfma_f32_32x32x16_bf16 v[50:65], v[216:219], v[86:89], v[50:65]
	ds_read_b64_tr_b16 v[216:217], v160 offset:24576
	ds_read_b64_tr_b16 v[218:219], v160 offset:26624
	s_waitcnt lgkmcnt(15)
	v_mfma_f32_32x32x16_bf16 v[50:65], v[220:223], v[66:69], v[50:65]
	ds_read_b64_tr_b16 v[220:221], v160 offset:28672
	ds_read_b64_tr_b16 v[222:223], v160 offset:30720
	s_waitcnt lgkmcnt(15)
	v_mfma_f32_32x32x16_bf16 v[50:65], v[224:227], v[70:73], v[50:65]
	ds_read_b64_tr_b16 v[224:225], v161 offset:16384
	ds_read_b64_tr_b16 v[226:227], v161 offset:18432
	s_waitcnt lgkmcnt(15)
	v_mfma_f32_32x32x16_bf16 v[34:49], v[228:231], v[82:85], v[34:49]
	ds_read_b64_tr_b16 v[228:229], v161 offset:20480
	ds_read_b64_tr_b16 v[230:231], v161 offset:22528
	s_waitcnt lgkmcnt(15)
	v_mfma_f32_32x32x16_bf16 v[34:49], v[232:235], v[86:89], v[34:49]
	ds_read_b64_tr_b16 v[232:233], v161 offset:24576
	ds_read_b64_tr_b16 v[234:235], v161 offset:26624
	s_waitcnt lgkmcnt(15)
	v_mfma_f32_32x32x16_bf16 v[34:49], v[236:239], v[66:69], v[34:49]
	ds_read_b64_tr_b16 v[236:237], v161 offset:28672
	ds_read_b64_tr_b16 v[238:239], v161 offset:30720
	s_waitcnt lgkmcnt(15)
	v_mfma_f32_32x32x16_bf16 v[34:49], v[240:243], v[70:73], v[34:49]
	s_waitcnt lgkmcnt(14)
	v_mfma_f32_32x32x16_bf16 v[18:33], v[244:247], v[82:85], v[18:33]
	s_waitcnt lgkmcnt(12)
	v_mfma_f32_32x32x16_bf16 v[18:33], v[212:215], v[86:89], v[18:33]
	s_waitcnt lgkmcnt(10)
	v_mfma_f32_32x32x16_bf16 v[18:33], v[216:219], v[66:69], v[18:33]
	s_waitcnt lgkmcnt(8)
	v_mfma_f32_32x32x16_bf16 v[18:33], v[220:223], v[70:73], v[18:33]
	s_waitcnt lgkmcnt(6)
	v_mfma_f32_32x32x16_bf16 v[2:17], v[224:227], v[82:85], v[2:17]
	s_waitcnt lgkmcnt(4)
	v_mfma_f32_32x32x16_bf16 v[2:17], v[228:231], v[86:89], v[2:17]
	s_waitcnt lgkmcnt(2)
	v_mfma_f32_32x32x16_bf16 v[2:17], v[232:235], v[66:69], v[2:17]
	s_waitcnt lgkmcnt(0)
	v_mfma_f32_32x32x16_bf16 v[2:17], v[236:239], v[70:73], v[2:17]
	s_nor_b64 s[26:27], s[38:39], s[46:47]
	s_and_saveexec_b64 s[2:3], s[26:27]
	s_cbranch_execnz .LBB0_346
	s_branch .LBB0_347

; DI f32x16 mfma32(bf16x8 a, bf16x8 b, f32x16 c) { return __builtin_amdgcn_mfma_f32_32x32x16_bf16(a, b, c, 0, 0, 0); }
; DI s16x4 vtr(lptr p) { return __builtin_bit_cast(s16x4, __builtin_amdgcn_ds_read_tr16_b64_v4i16((LAS s16x4*)p)); }
; template <int DQK, bool FOX>
; DI void attn_unit(const bf16_t* P, int pitch, int b, int qb, int qcol, int kcol, int vcol, bf16_t* Out, int opitch, int ocol, int gcol, const float* cum, lptr lds) {
;     ...
;             const float m_new = fmaxf(m_run, mx);
;             const float alpha = __builtin_amdgcn_exp2f(m_run - m_new);
;             const bool changed = __builtin_amdgcn_ballot_w64(m_new > m_run) != 0ull;
;             m_run = m_new;
;             float ls = 0.f;
; #pragma unroll
;             for (int t2 = 0; t2 < 2; ++t2)
; #pragma unroll
;                 for (int i = 0; i < 16; ++i) { const float e = __builtin_amdgcn_exp2f(pp[t2][i] - m_new); pp[t2][i] = e; ls += e; }
;             l_run = l_run * alpha + ls;
;             if (changed) {
; #pragma unroll
;                 for (int d = 0; d < 4; ++d) O[d] *= alpha;
;             }
;             bf16x8 pf[4];
; #pragma unroll
;             for (int s = 0; s < 4; ++s) pf[s] = pack8(pp[s >> 1], s & 1);
; #pragma unroll
;             for (int d = 0; d < 4; ++d)
; #pragma unroll
;                 for (int s = 0; s < 4; ++s) {
;                     const s16x4 lo = vtr(lds + (OFF_V + buf * REG + (16 * s) * 256) + vx[d]), hi = vtr(lds + (OFF_V + buf * REG + (16 * s + 8) * 256) + vx[d]);
;                     const bf16x8 vf = __builtin_shufflevector(lo, hi, 0, 1, 2, 3, 4, 5, 6, 7);
;                     O[d] = mfma32(vf, pf[s], O[d]);
.LBB0_356:
	v_pk_add_f32 v[82:83], v[82:83], v[182:183] op_sel_hi:[1,0] neg_lo:[0,1] neg_hi:[0,1]
	v_pk_add_f32 v[84:85], v[84:85], v[182:183] op_sel_hi:[1,0] neg_lo:[0,1] neg_hi:[0,1]
	v_pk_add_f32 v[86:87], v[86:87], v[182:183] op_sel_hi:[1,0] neg_lo:[0,1] neg_hi:[0,1]
	v_pk_add_f32 v[88:89], v[88:89], v[182:183] op_sel_hi:[1,0] neg_lo:[0,1] neg_hi:[0,1]
	v_pk_add_f32 v[90:91], v[90:91], v[182:183] op_sel_hi:[1,0] neg_lo:[0,1] neg_hi:[0,1]
	v_pk_add_f32 v[92:93], v[92:93], v[182:183] op_sel_hi:[1,0] neg_lo:[0,1] neg_hi:[0,1]
	v_pk_add_f32 v[94:95], v[94:95], v[182:183] op_sel_hi:[1,0] neg_lo:[0,1] neg_hi:[0,1]
	v_pk_add_f32 v[96:97], v[96:97], v[182:183] op_sel_hi:[1,0] neg_lo:[0,1] neg_hi:[0,1]
	v_pk_add_f32 v[66:67], v[66:67], v[182:183] op_sel_hi:[1,0] neg_lo:[0,1] neg_hi:[0,1]
	v_pk_add_f32 v[68:69], v[68:69], v[182:183] op_sel_hi:[1,0] neg_lo:[0,1] neg_hi:[0,1]
	v_pk_add_f32 v[70:71], v[70:71], v[182:183] op_sel_hi:[1,0] neg_lo:[0,1] neg_hi:[0,1]
	v_pk_add_f32 v[72:73], v[72:73], v[182:183] op_sel_hi:[1,0] neg_lo:[0,1] neg_hi:[0,1]
	v_pk_add_f32 v[74:75], v[74:75], v[182:183] op_sel_hi:[1,0] neg_lo:[0,1] neg_hi:[0,1]
	v_pk_add_f32 v[76:77], v[76:77], v[182:183] op_sel_hi:[1,0] neg_lo:[0,1] neg_hi:[0,1]
	v_pk_add_f32 v[78:79], v[78:79], v[182:183] op_sel_hi:[1,0] neg_lo:[0,1] neg_hi:[0,1]
	v_pk_add_f32 v[80:81], v[80:81], v[182:183] op_sel_hi:[1,0] neg_lo:[0,1] neg_hi:[0,1]
	v_exp_f32_e32 v82, v82
	v_exp_f32_e32 v83, v83
	v_exp_f32_e32 v84, v84
	v_exp_f32_e32 v85, v85
	v_exp_f32_e32 v86, v86
	v_exp_f32_e32 v87, v87
	v_exp_f32_e32 v88, v88
	v_exp_f32_e32 v89, v89
	v_exp_f32_e32 v90, v90
	v_exp_f32_e32 v91, v91
	v_exp_f32_e32 v92, v92
	v_exp_f32_e32 v93, v93
	v_exp_f32_e32 v94, v94
	v_exp_f32_e32 v95, v95
	v_exp_f32_e32 v96, v96
	v_exp_f32_e32 v97, v97
	v_exp_f32_e32 v66, v66
	v_exp_f32_e32 v67, v67
	v_exp_f32_e32 v68, v68
	v_exp_f32_e32 v69, v69
	v_exp_f32_e32 v70, v70
	v_exp_f32_e32 v71, v71
	v_exp_f32_e32 v72, v72
	v_exp_f32_e32 v73, v73
	v_exp_f32_e32 v74, v74
	v_exp_f32_e32 v75, v75
	v_exp_f32_e32 v76, v76
	v_exp_f32_e32 v77, v77
	v_exp_f32_e32 v78, v78
	v_exp_f32_e32 v79, v79
	v_exp_f32_e32 v80, v80
	v_exp_f32_e32 v81, v81
	v_pk_add_f32 v[184:185], v[82:83], v[84:85]
	v_pk_add_f32 v[184:185], v[184:185], v[86:87]
	v_pk_add_f32 v[184:185], v[184:185], v[88:89]
	v_pk_add_f32 v[184:185], v[184:185], v[90:91]
	v_pk_add_f32 v[184:185], v[184:185], v[92:93]
	v_pk_add_f32 v[184:185], v[184:185], v[94:95]
	v_pk_add_f32 v[184:185], v[184:185], v[96:97]
	v_pk_add_f32 v[184:185], v[184:185], v[66:67]
	v_pk_add_f32 v[184:185], v[184:185], v[68:69]
	v_pk_add_f32 v[184:185], v[184:185], v[70:71]
	v_pk_add_f32 v[184:185], v[184:185], v[72:73]
	v_pk_add_f32 v[184:185], v[184:185], v[74:75]
	v_pk_add_f32 v[184:185], v[184:185], v[76:77]
	v_pk_add_f32 v[184:185], v[184:185], v[78:79]
	v_pk_add_f32 v[184:185], v[184:185], v[80:81]
	v_add_f32_e32 v184, v184, v185
	v_fmac_f32_e32 v184, v181, v0
	v_mov_b32_e32 v181, v184
	v_cvt_pk_bf16_f32 v82, v82, v83
	v_cvt_pk_bf16_f32 v83, v84, v85
	v_cvt_pk_bf16_f32 v84, v86, v87
	v_cvt_pk_bf16_f32 v85, v88, v89
	v_cvt_pk_bf16_f32 v86, v90, v91
	v_cvt_pk_bf16_f32 v87, v92, v93
	v_cvt_pk_bf16_f32 v88, v94, v95
	v_cvt_pk_bf16_f32 v89, v96, v97
	v_cvt_pk_bf16_f32 v66, v66, v67
	v_cvt_pk_bf16_f32 v67, v68, v69
	v_cvt_pk_bf16_f32 v68, v70, v71
	v_cvt_pk_bf16_f32 v69, v72, v73
	v_cvt_pk_bf16_f32 v70, v74, v75
	v_cvt_pk_bf16_f32 v71, v76, v77
	v_cvt_pk_bf16_f32 v72, v78, v79
	v_cvt_pk_bf16_f32 v73, v80, v81
	s_waitcnt lgkmcnt(15)
	v_mfma_f32_32x32x16_bf16 v[50:65], v[212:215], v[82:85], v[50:65]
	ds_read_b64_tr_b16 v[212:213], v160 offset:53248
	ds_read_b64_tr_b16 v[214:215], v160 offset:55296
	s_waitcnt lgkmcnt(15)
	v_mfma_f32_32x32x16_bf16 v[50:65], v[216:219], v[86:89], v[50:65]
	ds_read_b64_tr_b16 v[216:217], v160 offset:57344
	ds_read_b64_tr_b16 v[218:219], v160 offset:59392
	s_waitcnt lgkmcnt(15)
	v_mfma_f32_32x32x16_bf16 v[50:65], v[220:223], v[66:69], v[50:65]
	ds_read_b64_tr_b16 v[220:221], v160 offset:61440
	ds_read_b64_tr_b16 v[222:223], v160 offset:63488
	s_waitcnt lgkmcnt(15)
	v_mfma_f32_32x32x16_bf16 v[50:65], v[224:227], v[70:73], v[50:65]
	ds_read_b64_tr_b16 v[224:225], v161 offset:49152
	ds_read_b64_tr_b16 v[226:227], v161 offset:51200
	s_waitcnt lgkmcnt(15)
	v_mfma_f32_32x32x16_bf16 v[34:49], v[228:231], v[82:85], v[34:49]
	ds_read_b64_tr_b16 v[228:229], v161 offset:53248
	ds_read_b64_tr_b16 v[230:231], v161 offset:55296
	s_waitcnt lgkmcnt(15)
	v_mfma_f32_32x32x16_bf16 v[34:49], v[232:235], v[86:89], v[34:49]
	ds_read_b64_tr_b16 v[232:233], v161 offset:57344
	ds_read_b64_tr_b16 v[234:235], v161 offset:59392
	s_waitcnt lgkmcnt(15)
	v_mfma_f32_32x32x16_bf16 v[34:49], v[236:239], v[66:69], v[34:49]
	ds_read_b64_tr_b16 v[236:237], v161 offset:61440
	ds_read_b64_tr_b16 v[238:239], v161 offset:63488
	s_waitcnt lgkmcnt(15)
	v_mfma_f32_32x32x16_bf16 v[34:49], v[240:243], v[70:73], v[34:49]
	s_waitcnt lgkmcnt(14)
	v_mfma_f32_32x32x16_bf16 v[18:33], v[244:247], v[82:85], v[18:33]
	s_waitcnt lgkmcnt(12)
	v_mfma_f32_32x32x16_bf16 v[18:33], v[212:215], v[86:89], v[18:33]
	s_waitcnt lgkmcnt(10)
	v_mfma_f32_32x32x16_bf16 v[18:33], v[216:219], v[66:69], v[18:33]
	s_waitcnt lgkmcnt(8)
	v_mfma_f32_32x32x16_bf16 v[18:33], v[220:223], v[70:73], v[18:33]
	s_waitcnt lgkmcnt(6)
	v_mfma_f32_32x32x16_bf16 v[2:17], v[224:227], v[82:85], v[2:17]
	s_waitcnt lgkmcnt(4)
	v_mfma_f32_32x32x16_bf16 v[2:17], v[228:231], v[86:89], v[2:17]
	s_waitcnt lgkmcnt(2)
	v_mfma_f32_32x32x16_bf16 v[2:17], v[232:235], v[66:69], v[2:17]
	s_waitcnt lgkmcnt(0)
	v_mfma_f32_32x32x16_bf16 v[2:17], v[236:239], v[70:73], v[2:17]
	s_nor_b64 s[26:27], s[38:39], s[46:47]
	s_and_saveexec_b64 s[2:3], s[26:27]
	s_cbranch_execz .LBB0_334
	s_branch .LBB0_333

; DI f32x16 mfma32(bf16x8 a, bf16x8 b, f32x16 c) { return __builtin_amdgcn_mfma_f32_32x32x16_bf16(a, b, c, 0, 0, 0); }
; DI s16x4 vtr(lptr p) { return __builtin_bit_cast(s16x4, __builtin_amdgcn_ds_read_tr16_b64_v4i16((LAS s16x4*)p)); }
; template <int DQK, bool FOX>
; DI void attn_unit(const bf16_t* P, int pitch, int b, int qb, int qcol, int kcol, int vcol, bf16_t* Out, int opitch, int ocol, int gcol, const float* cum, lptr lds) {
;     ...
;             const float m_new = fmaxf(m_run, mx);
;             const float alpha = __builtin_amdgcn_exp2f(m_run - m_new);
;             const bool changed = __builtin_amdgcn_ballot_w64(m_new > m_run) != 0ull;
;             m_run = m_new;
;             float ls = 0.f;
; #pragma unroll
;             for (int t2 = 0; t2 < 2; ++t2)
; #pragma unroll
;                 for (int i = 0; i < 16; ++i) { const float e = __builtin_amdgcn_exp2f(pp[t2][i] - m_new); pp[t2][i] = e; ls += e; }
;             l_run = l_run * alpha + ls;
;             if (changed) {
; #pragma unroll
;                 for (int d = 0; d < 4; ++d) O[d] *= alpha;
;             }
;             bf16x8 pf[4];
; #pragma unroll
;             for (int s = 0; s < 4; ++s) pf[s] = pack8(pp[s >> 1], s & 1);
; #pragma unroll
;             for (int d = 0; d < 4; ++d)
; #pragma unroll
;                 for (int s = 0; s < 4; ++s) {
;                     const s16x4 lo = vtr(lds + (OFF_V + buf * REG + (16 * s) * 256) + vx[d]), hi = vtr(lds + (OFF_V + buf * REG + (16 * s + 8) * 256) + vx[d]);
;                     const bf16x8 vf = __builtin_shufflevector(lo, hi, 0, 1, 2, 3, 4, 5, 6, 7);
;                     O[d] = mfma32(vf, pf[s], O[d]);
.LBB0_541:
	v_pk_add_f32 v[82:83], v[82:83], v[134:135] op_sel_hi:[1,0] neg_lo:[0,1] neg_hi:[0,1]
	v_pk_add_f32 v[84:85], v[84:85], v[134:135] op_sel_hi:[1,0] neg_lo:[0,1] neg_hi:[0,1]
	v_pk_add_f32 v[86:87], v[86:87], v[134:135] op_sel_hi:[1,0] neg_lo:[0,1] neg_hi:[0,1]
	v_pk_add_f32 v[88:89], v[88:89], v[134:135] op_sel_hi:[1,0] neg_lo:[0,1] neg_hi:[0,1]
	v_pk_add_f32 v[90:91], v[90:91], v[134:135] op_sel_hi:[1,0] neg_lo:[0,1] neg_hi:[0,1]
	v_pk_add_f32 v[92:93], v[92:93], v[134:135] op_sel_hi:[1,0] neg_lo:[0,1] neg_hi:[0,1]
	v_pk_add_f32 v[94:95], v[94:95], v[134:135] op_sel_hi:[1,0] neg_lo:[0,1] neg_hi:[0,1]
	v_pk_add_f32 v[96:97], v[96:97], v[134:135] op_sel_hi:[1,0] neg_lo:[0,1] neg_hi:[0,1]
	v_pk_add_f32 v[66:67], v[66:67], v[134:135] op_sel_hi:[1,0] neg_lo:[0,1] neg_hi:[0,1]
	v_pk_add_f32 v[68:69], v[68:69], v[134:135] op_sel_hi:[1,0] neg_lo:[0,1] neg_hi:[0,1]
	v_pk_add_f32 v[70:71], v[70:71], v[134:135] op_sel_hi:[1,0] neg_lo:[0,1] neg_hi:[0,1]
	v_pk_add_f32 v[72:73], v[72:73], v[134:135] op_sel_hi:[1,0] neg_lo:[0,1] neg_hi:[0,1]
	v_pk_add_f32 v[74:75], v[74:75], v[134:135] op_sel_hi:[1,0] neg_lo:[0,1] neg_hi:[0,1]
	v_pk_add_f32 v[76:77], v[76:77], v[134:135] op_sel_hi:[1,0] neg_lo:[0,1] neg_hi:[0,1]
	v_pk_add_f32 v[78:79], v[78:79], v[134:135] op_sel_hi:[1,0] neg_lo:[0,1] neg_hi:[0,1]
	v_pk_add_f32 v[80:81], v[80:81], v[134:135] op_sel_hi:[1,0] neg_lo:[0,1] neg_hi:[0,1]
	v_exp_f32_e32 v82, v82
	v_exp_f32_e32 v83, v83
	v_exp_f32_e32 v84, v84
	v_exp_f32_e32 v85, v85
	v_exp_f32_e32 v86, v86
	v_exp_f32_e32 v87, v87
	v_exp_f32_e32 v88, v88
	v_exp_f32_e32 v89, v89
	v_exp_f32_e32 v90, v90
	v_exp_f32_e32 v91, v91
	v_exp_f32_e32 v92, v92
	v_exp_f32_e32 v93, v93
	v_exp_f32_e32 v94, v94
	v_exp_f32_e32 v95, v95
	v_exp_f32_e32 v96, v96
	v_exp_f32_e32 v97, v97
	v_exp_f32_e32 v66, v66
	v_exp_f32_e32 v67, v67
	v_exp_f32_e32 v68, v68
	v_exp_f32_e32 v69, v69
	v_exp_f32_e32 v70, v70
	v_exp_f32_e32 v71, v71
	v_exp_f32_e32 v72, v72
	v_exp_f32_e32 v73, v73
	v_exp_f32_e32 v74, v74
	v_exp_f32_e32 v75, v75
	v_exp_f32_e32 v76, v76
	v_exp_f32_e32 v77, v77
	v_exp_f32_e32 v78, v78
	v_exp_f32_e32 v79, v79
	v_exp_f32_e32 v80, v80
	v_exp_f32_e32 v81, v81
	v_pk_add_f32 v[136:137], v[82:83], v[84:85]
	v_pk_add_f32 v[136:137], v[136:137], v[86:87]
	v_pk_add_f32 v[136:137], v[136:137], v[88:89]
	v_pk_add_f32 v[136:137], v[136:137], v[90:91]
	v_pk_add_f32 v[136:137], v[136:137], v[92:93]
	v_pk_add_f32 v[136:137], v[136:137], v[94:95]
	v_pk_add_f32 v[136:137], v[136:137], v[96:97]
	v_pk_add_f32 v[136:137], v[136:137], v[66:67]
	v_pk_add_f32 v[136:137], v[136:137], v[68:69]
	v_pk_add_f32 v[136:137], v[136:137], v[70:71]
	v_pk_add_f32 v[136:137], v[136:137], v[72:73]
	v_pk_add_f32 v[136:137], v[136:137], v[74:75]
	v_pk_add_f32 v[136:137], v[136:137], v[76:77]
	v_pk_add_f32 v[136:137], v[136:137], v[78:79]
	v_pk_add_f32 v[136:137], v[136:137], v[80:81]
	v_add_f32_e32 v136, v136, v137
	v_fmac_f32_e32 v136, v132, v0
	v_mov_b32_e32 v132, v136
	v_cvt_pk_bf16_f32 v82, v82, v83
	v_cvt_pk_bf16_f32 v83, v84, v85
	v_cvt_pk_bf16_f32 v84, v86, v87
	v_cvt_pk_bf16_f32 v85, v88, v89
	v_cvt_pk_bf16_f32 v86, v90, v91
	v_cvt_pk_bf16_f32 v87, v92, v93
	v_cvt_pk_bf16_f32 v88, v94, v95
	v_cvt_pk_bf16_f32 v89, v96, v97
	v_cvt_pk_bf16_f32 v66, v66, v67
	v_cvt_pk_bf16_f32 v67, v68, v69
	v_cvt_pk_bf16_f32 v68, v70, v71
	v_cvt_pk_bf16_f32 v69, v72, v73
	v_cvt_pk_bf16_f32 v70, v74, v75
	v_cvt_pk_bf16_f32 v71, v76, v77
	v_cvt_pk_bf16_f32 v72, v78, v79
	v_cvt_pk_bf16_f32 v73, v80, v81
	s_waitcnt lgkmcnt(15)
	v_mfma_f32_32x32x16_bf16 v[50:65], v[212:215], v[82:85], v[50:65]
	ds_read_b64_tr_b16 v[212:213], v129 offset:12288
	ds_read_b64_tr_b16 v[214:215], v129 offset:14336
	s_waitcnt lgkmcnt(15)
	v_mfma_f32_32x32x16_bf16 v[50:65], v[216:219], v[86:89], v[50:65]
	ds_read_b64_tr_b16 v[216:217], v129 offset:16384
	ds_read_b64_tr_b16 v[218:219], v129 offset:18432
	s_waitcnt lgkmcnt(15)
	v_mfma_f32_32x32x16_bf16 v[50:65], v[220:223], v[66:69], v[50:65]
	ds_read_b64_tr_b16 v[220:221], v129 offset:20480
	ds_read_b64_tr_b16 v[222:223], v129 offset:22528
	s_waitcnt lgkmcnt(15)
	v_mfma_f32_32x32x16_bf16 v[50:65], v[224:227], v[70:73], v[50:65]
	ds_read_b64_tr_b16 v[224:225], v130 offset:8192
	ds_read_b64_tr_b16 v[226:227], v130 offset:10240
	s_waitcnt lgkmcnt(15)
	v_mfma_f32_32x32x16_bf16 v[34:49], v[228:231], v[82:85], v[34:49]
	ds_read_b64_tr_b16 v[228:229], v130 offset:12288
	ds_read_b64_tr_b16 v[230:231], v130 offset:14336
	s_waitcnt lgkmcnt(15)
	v_mfma_f32_32x32x16_bf16 v[34:49], v[232:235], v[86:89], v[34:49]
	ds_read_b64_tr_b16 v[232:233], v130 offset:16384
	ds_read_b64_tr_b16 v[234:235], v130 offset:18432
	s_waitcnt lgkmcnt(15)
	v_mfma_f32_32x32x16_bf16 v[34:49], v[236:239], v[66:69], v[34:49]
	ds_read_b64_tr_b16 v[236:237], v130 offset:20480
	ds_read_b64_tr_b16 v[238:239], v130 offset:22528
	s_waitcnt lgkmcnt(15)
	v_mfma_f32_32x32x16_bf16 v[34:49], v[240:243], v[70:73], v[34:49]
	s_waitcnt lgkmcnt(14)
	v_mfma_f32_32x32x16_bf16 v[18:33], v[244:247], v[82:85], v[18:33]
	s_waitcnt lgkmcnt(12)
	v_mfma_f32_32x32x16_bf16 v[18:33], v[212:215], v[86:89], v[18:33]
	s_waitcnt lgkmcnt(10)
	v_mfma_f32_32x32x16_bf16 v[18:33], v[216:219], v[66:69], v[18:33]
	s_waitcnt lgkmcnt(8)
	v_mfma_f32_32x32x16_bf16 v[18:33], v[220:223], v[70:73], v[18:33]
	s_waitcnt lgkmcnt(6)
	v_mfma_f32_32x32x16_bf16 v[2:17], v[224:227], v[82:85], v[2:17]
	s_waitcnt lgkmcnt(4)
	v_mfma_f32_32x32x16_bf16 v[2:17], v[228:231], v[86:89], v[2:17]
	s_waitcnt lgkmcnt(2)
	v_mfma_f32_32x32x16_bf16 v[2:17], v[232:235], v[66:69], v[2:17]
	s_waitcnt lgkmcnt(0)
	v_mfma_f32_32x32x16_bf16 v[2:17], v[236:239], v[70:73], v[2:17]
	s_branch .LBB0_543

; DI f32x16 mfma32(bf16x8 a, bf16x8 b, f32x16 c) { return __builtin_amdgcn_mfma_f32_32x32x16_bf16(a, b, c, 0, 0, 0); }
; DI s16x4 vtr(lptr p) { return __builtin_bit_cast(s16x4, __builtin_amdgcn_ds_read_tr16_b64_v4i16((LAS s16x4*)p)); }
; template <int DQK, bool FOX>
; DI void attn_unit(const bf16_t* P, int pitch, int b, int qb, int qcol, int kcol, int vcol, bf16_t* Out, int opitch, int ocol, int gcol, const float* cum, lptr lds) {
;     ...
;             const float m_new = fmaxf(m_run, mx);
;             const float alpha = __builtin_amdgcn_exp2f(m_run - m_new);
;             const bool changed = __builtin_amdgcn_ballot_w64(m_new > m_run) != 0ull;
;             m_run = m_new;
;             float ls = 0.f;
; #pragma unroll
;             for (int t2 = 0; t2 < 2; ++t2)
; #pragma unroll
;                 for (int i = 0; i < 16; ++i) { const float e = __builtin_amdgcn_exp2f(pp[t2][i] - m_new); pp[t2][i] = e; ls += e; }
;             l_run = l_run * alpha + ls;
;             if (changed) {
; #pragma unroll
;                 for (int d = 0; d < 4; ++d) O[d] *= alpha;
;             }
;             bf16x8 pf[4];
; #pragma unroll
;             for (int s = 0; s < 4; ++s) pf[s] = pack8(pp[s >> 1], s & 1);
; #pragma unroll
;             for (int d = 0; d < 4; ++d)
; #pragma unroll
;                 for (int s = 0; s < 4; ++s) {
;                     const s16x4 lo = vtr(lds + (OFF_V + buf * REG + (16 * s) * 256) + vx[d]), hi = vtr(lds + (OFF_V + buf * REG + (16 * s + 8) * 256) + vx[d]);
;                     const bf16x8 vf = __builtin_shufflevector(lo, hi, 0, 1, 2, 3, 4, 5, 6, 7);
;                     O[d] = mfma32(vf, pf[s], O[d]);
.LBB0_550:
	v_pk_add_f32 v[82:83], v[82:83], v[132:133] op_sel:[0,1] op_sel_hi:[1,1] neg_lo:[0,1] neg_hi:[0,1]
	v_pk_add_f32 v[84:85], v[84:85], v[132:133] op_sel:[0,1] op_sel_hi:[1,1] neg_lo:[0,1] neg_hi:[0,1]
	v_pk_add_f32 v[86:87], v[86:87], v[132:133] op_sel:[0,1] op_sel_hi:[1,1] neg_lo:[0,1] neg_hi:[0,1]
	v_pk_add_f32 v[88:89], v[88:89], v[132:133] op_sel:[0,1] op_sel_hi:[1,1] neg_lo:[0,1] neg_hi:[0,1]
	v_pk_add_f32 v[90:91], v[90:91], v[132:133] op_sel:[0,1] op_sel_hi:[1,1] neg_lo:[0,1] neg_hi:[0,1]
	v_pk_add_f32 v[92:93], v[92:93], v[132:133] op_sel:[0,1] op_sel_hi:[1,1] neg_lo:[0,1] neg_hi:[0,1]
	v_pk_add_f32 v[94:95], v[94:95], v[132:133] op_sel:[0,1] op_sel_hi:[1,1] neg_lo:[0,1] neg_hi:[0,1]
	v_pk_add_f32 v[96:97], v[96:97], v[132:133] op_sel:[0,1] op_sel_hi:[1,1] neg_lo:[0,1] neg_hi:[0,1]
	v_pk_add_f32 v[66:67], v[66:67], v[132:133] op_sel:[0,1] op_sel_hi:[1,1] neg_lo:[0,1] neg_hi:[0,1]
	v_pk_add_f32 v[68:69], v[68:69], v[132:133] op_sel:[0,1] op_sel_hi:[1,1] neg_lo:[0,1] neg_hi:[0,1]
	v_pk_add_f32 v[70:71], v[70:71], v[132:133] op_sel:[0,1] op_sel_hi:[1,1] neg_lo:[0,1] neg_hi:[0,1]
	v_pk_add_f32 v[72:73], v[72:73], v[132:133] op_sel:[0,1] op_sel_hi:[1,1] neg_lo:[0,1] neg_hi:[0,1]
	v_pk_add_f32 v[74:75], v[74:75], v[132:133] op_sel:[0,1] op_sel_hi:[1,1] neg_lo:[0,1] neg_hi:[0,1]
	v_pk_add_f32 v[76:77], v[76:77], v[132:133] op_sel:[0,1] op_sel_hi:[1,1] neg_lo:[0,1] neg_hi:[0,1]
	v_pk_add_f32 v[78:79], v[78:79], v[132:133] op_sel:[0,1] op_sel_hi:[1,1] neg_lo:[0,1] neg_hi:[0,1]
	v_pk_add_f32 v[80:81], v[80:81], v[132:133] op_sel:[0,1] op_sel_hi:[1,1] neg_lo:[0,1] neg_hi:[0,1]
	v_exp_f32_e32 v82, v82
	v_exp_f32_e32 v83, v83
	v_exp_f32_e32 v84, v84
	v_exp_f32_e32 v85, v85
	v_exp_f32_e32 v86, v86
	v_exp_f32_e32 v87, v87
	v_exp_f32_e32 v88, v88
	v_exp_f32_e32 v89, v89
	v_exp_f32_e32 v90, v90
	v_exp_f32_e32 v91, v91
	v_exp_f32_e32 v92, v92
	v_exp_f32_e32 v93, v93
	v_exp_f32_e32 v94, v94
	v_exp_f32_e32 v95, v95
	v_exp_f32_e32 v96, v96
	v_exp_f32_e32 v97, v97
	v_exp_f32_e32 v66, v66
	v_exp_f32_e32 v67, v67
	v_exp_f32_e32 v68, v68
	v_exp_f32_e32 v69, v69
	v_exp_f32_e32 v70, v70
	v_exp_f32_e32 v71, v71
	v_exp_f32_e32 v72, v72
	v_exp_f32_e32 v73, v73
	v_exp_f32_e32 v74, v74
	v_exp_f32_e32 v75, v75
	v_exp_f32_e32 v76, v76
	v_exp_f32_e32 v77, v77
	v_exp_f32_e32 v78, v78
	v_exp_f32_e32 v79, v79
	v_exp_f32_e32 v80, v80
	v_exp_f32_e32 v81, v81
	v_pk_add_f32 v[136:137], v[82:83], v[84:85]
	v_pk_add_f32 v[136:137], v[136:137], v[86:87]
	v_pk_add_f32 v[136:137], v[136:137], v[88:89]
	v_pk_add_f32 v[136:137], v[136:137], v[90:91]
	v_pk_add_f32 v[136:137], v[136:137], v[92:93]
	v_pk_add_f32 v[136:137], v[136:137], v[94:95]
	v_pk_add_f32 v[136:137], v[136:137], v[96:97]
	v_pk_add_f32 v[136:137], v[136:137], v[66:67]
	v_pk_add_f32 v[136:137], v[136:137], v[68:69]
	v_pk_add_f32 v[136:137], v[136:137], v[70:71]
	v_pk_add_f32 v[136:137], v[136:137], v[72:73]
	v_pk_add_f32 v[136:137], v[136:137], v[74:75]
	v_pk_add_f32 v[136:137], v[136:137], v[76:77]
	v_pk_add_f32 v[136:137], v[136:137], v[78:79]
	v_pk_add_f32 v[136:137], v[136:137], v[80:81]
	v_add_f32_e32 v136, v136, v137
	v_fmac_f32_e32 v136, v132, v0
	v_mov_b32_e32 v132, v136
	v_cvt_pk_bf16_f32 v82, v82, v83
	v_cvt_pk_bf16_f32 v83, v84, v85
	v_cvt_pk_bf16_f32 v84, v86, v87
	v_cvt_pk_bf16_f32 v85, v88, v89
	v_cvt_pk_bf16_f32 v86, v90, v91
	v_cvt_pk_bf16_f32 v87, v92, v93
	v_cvt_pk_bf16_f32 v88, v94, v95
	v_cvt_pk_bf16_f32 v89, v96, v97
	v_cvt_pk_bf16_f32 v66, v66, v67
	v_cvt_pk_bf16_f32 v67, v68, v69
	v_cvt_pk_bf16_f32 v68, v70, v71
	v_cvt_pk_bf16_f32 v69, v72, v73
	v_cvt_pk_bf16_f32 v70, v74, v75
	v_cvt_pk_bf16_f32 v71, v76, v77
	v_cvt_pk_bf16_f32 v72, v78, v79
	v_cvt_pk_bf16_f32 v73, v80, v81
	s_waitcnt lgkmcnt(15)
	v_mfma_f32_32x32x16_bf16 v[50:65], v[212:215], v[82:85], v[50:65]
	ds_read_b64_tr_b16 v[212:213], v129 offset:36864
	ds_read_b64_tr_b16 v[214:215], v129 offset:38912
	s_waitcnt lgkmcnt(15)
	v_mfma_f32_32x32x16_bf16 v[50:65], v[216:219], v[86:89], v[50:65]
	ds_read_b64_tr_b16 v[216:217], v129 offset:40960
	ds_read_b64_tr_b16 v[218:219], v129 offset:43008
	s_waitcnt lgkmcnt(15)
	v_mfma_f32_32x32x16_bf16 v[50:65], v[220:223], v[66:69], v[50:65]
	ds_read_b64_tr_b16 v[220:221], v129 offset:45056
	ds_read_b64_tr_b16 v[222:223], v129 offset:47104
	s_waitcnt lgkmcnt(15)
	v_mfma_f32_32x32x16_bf16 v[50:65], v[224:227], v[70:73], v[50:65]
	ds_read_b64_tr_b16 v[224:225], v130 offset:32768
	ds_read_b64_tr_b16 v[226:227], v130 offset:34816
	s_waitcnt lgkmcnt(15)
	v_mfma_f32_32x32x16_bf16 v[34:49], v[228:231], v[82:85], v[34:49]
	ds_read_b64_tr_b16 v[228:229], v130 offset:36864
	ds_read_b64_tr_b16 v[230:231], v130 offset:38912
	s_waitcnt lgkmcnt(15)
	v_mfma_f32_32x32x16_bf16 v[34:49], v[232:235], v[86:89], v[34:49]
	ds_read_b64_tr_b16 v[232:233], v130 offset:40960
	ds_read_b64_tr_b16 v[234:235], v130 offset:43008
	s_waitcnt lgkmcnt(15)
	v_mfma_f32_32x32x16_bf16 v[34:49], v[236:239], v[66:69], v[34:49]
	ds_read_b64_tr_b16 v[236:237], v130 offset:45056
	ds_read_b64_tr_b16 v[238:239], v130 offset:47104
	s_waitcnt lgkmcnt(15)
	v_mfma_f32_32x32x16_bf16 v[34:49], v[240:243], v[70:73], v[34:49]
	s_waitcnt lgkmcnt(14)
	v_mfma_f32_32x32x16_bf16 v[18:33], v[244:247], v[82:85], v[18:33]
	s_waitcnt lgkmcnt(12)
	v_mfma_f32_32x32x16_bf16 v[18:33], v[212:215], v[86:89], v[18:33]
	s_waitcnt lgkmcnt(10)
	v_mfma_f32_32x32x16_bf16 v[18:33], v[216:219], v[66:69], v[18:33]
	s_waitcnt lgkmcnt(8)
	v_mfma_f32_32x32x16_bf16 v[18:33], v[220:223], v[70:73], v[18:33]
	s_waitcnt lgkmcnt(6)
	v_mfma_f32_32x32x16_bf16 v[2:17], v[224:227], v[82:85], v[2:17]
	s_waitcnt lgkmcnt(4)
	v_mfma_f32_32x32x16_bf16 v[2:17], v[228:231], v[86:89], v[2:17]
	s_waitcnt lgkmcnt(2)
	v_mfma_f32_32x32x16_bf16 v[2:17], v[232:235], v[66:69], v[2:17]
	s_waitcnt lgkmcnt(0)
	v_mfma_f32_32x32x16_bf16 v[2:17], v[236:239], v[70:73], v[2:17]
	s_branch .LBB0_533
